# grid barriers: follower workgroups invalidate their L1 at arrival (polls bypass L1, nothing else is loaded while spinning); the XCD leader still invalidates after the top-level barrier completes
# speedup vs baseline: 1.0265x; 1.0096x over previous
.LBB0_193:
	s_mov_b64 s[28:29], exec
	v_mbcnt_lo_u32_b32 v0, s28, 0
	v_mbcnt_hi_u32_b32 v0, s29, v0
	v_cmp_eq_u32_e32 vcc, 0, v0
	s_and_saveexec_b64 s[18:19], vcc
	s_cbranch_execz .LBB0_195
	s_bcnt1_i32_b64 s1, s[28:29]
	v_readlane_b32 s24, v253, 37
	v_mov_b32_e32 v4, s1
	v_readlane_b32 s25, v253, 38
	s_nop 4
	global_atomic_add v4, v1, v4, s[24:25] sc0
	buffer_inv sc1

.LBB0_208:
	s_or_b64 exec, exec, s[28:29]
	s_waitcnt vmcnt(0)
	s_waitcnt vmcnt(0)

.LBB0_422:
	buffer_inv sc1
	s_or_b64 exec, exec, s[18:19]
	v_cvt_f32_u32_e32 v5, v3
	s_waitcnt vmcnt(0)
	v_readfirstlane_b32 s1, v4
	v_sub_u32_e32 v4, 0, v3
	v_rcp_iflag_f32_e32 v5, v5
	v_add_u32_e32 v6, s1, v0
	v_mul_f32_e32 v5, 0x4f7ffffe, v5
	v_cvt_u32_f32_e32 v5, v5
	v_mul_lo_u32 v0, v4, v5
	v_mul_hi_u32 v0, v5, v0
	v_add_u32_e32 v0, v5, v0
	v_mul_hi_u32 v0, v6, v0
	v_mul_lo_u32 v4, v0, v3
	v_sub_u32_e32 v4, v6, v4
	v_add_u32_e32 v5, 1, v0
	v_cmp_ge_u32_e32 vcc, v4, v3
	s_nop 1
	v_cndmask_b32_e32 v0, v0, v5, vcc
	v_sub_u32_e32 v5, v4, v3
	v_cndmask_b32_e32 v4, v4, v5, vcc
	v_add_u32_e32 v5, 1, v0
	v_cmp_ge_u32_e32 vcc, v4, v3
	v_add_u32_e32 v4, 1, v6
	s_nop 0
	v_cndmask_b32_e32 v0, v0, v5, vcc
	v_mul_lo_u32 v5, v3, v0
	v_add_u32_e32 v3, v5, v3
	v_cmp_ne_u32_e32 vcc, v4, v3
	s_and_saveexec_b64 s[18:19], vcc
	s_xor_b64 s[18:19], exec, s[18:19]
	s_cbranch_execz .LBB0_436
	s_waitcnt lgkmcnt(0)
	global_load_dword v2, v1, s[54:55] sc1
	s_waitcnt vmcnt(0)
	v_cmp_eq_u32_e32 vcc, v2, v0
	s_and_saveexec_b64 s[28:29], vcc
	s_cbranch_execz .LBB0_435
	s_mov_b32 s1, 1
	s_mov_b64 s[30:31], 0
	s_branch .LBB0_426

.LBB0_908:
	s_or_b64 exec, exec, s[18:19]
	buffer_inv sc1
	v_cvt_f32_u32_e32 v5, v3
	s_waitcnt vmcnt(0)
	v_readfirstlane_b32 s1, v4
	v_sub_u32_e32 v4, 0, v3
	v_rcp_iflag_f32_e32 v5, v5
	v_add_u32_e32 v6, s1, v0
	v_mul_f32_e32 v5, 0x4f7ffffe, v5
	v_cvt_u32_f32_e32 v5, v5
	v_mul_lo_u32 v0, v4, v5
	v_mul_hi_u32 v0, v5, v0
	v_add_u32_e32 v0, v5, v0
	v_mul_hi_u32 v0, v6, v0
	v_mul_lo_u32 v4, v0, v3
	v_sub_u32_e32 v4, v6, v4
	v_add_u32_e32 v5, 1, v0
	v_cmp_ge_u32_e32 vcc, v4, v3
	s_nop 1
	v_cndmask_b32_e32 v0, v0, v5, vcc
	v_sub_u32_e32 v5, v4, v3
	v_cndmask_b32_e32 v4, v4, v5, vcc
	v_add_u32_e32 v5, 1, v0
	v_cmp_ge_u32_e32 vcc, v4, v3
	v_add_u32_e32 v4, 1, v6
	s_nop 0
	v_cndmask_b32_e32 v0, v0, v5, vcc
	v_mul_lo_u32 v5, v3, v0
	v_add_u32_e32 v3, v5, v3
	v_cmp_ne_u32_e32 vcc, v4, v3
	s_and_saveexec_b64 s[18:19], vcc
	s_xor_b64 s[18:19], exec, s[18:19]
	s_cbranch_execz .LBB0_922
	s_waitcnt lgkmcnt(0)
	global_load_dword v2, v1, s[54:55] sc1
	s_waitcnt vmcnt(0)
	v_cmp_eq_u32_e32 vcc, v2, v0
	s_and_saveexec_b64 s[24:25], vcc
	s_cbranch_execz .LBB0_921
	s_mov_b32 s1, 1
	s_mov_b64 s[26:27], 0
	s_branch .LBB0_912

.LBB0_921:
	s_or_b64 exec, exec, s[24:25]
	s_waitcnt vmcnt(0)
	s_waitcnt vmcnt(0)

.LBB0_1044:
	s_or_b64 exec, exec, s[18:19]
	v_cvt_f32_u32_e32 v5, v3
	buffer_inv sc1
	s_waitcnt vmcnt(0)
	v_readfirstlane_b32 s1, v4
	v_sub_u32_e32 v4, 0, v3
	v_rcp_iflag_f32_e32 v5, v5
	v_add_u32_e32 v6, s1, v0
	v_mul_f32_e32 v5, 0x4f7ffffe, v5
	v_cvt_u32_f32_e32 v5, v5
	v_mul_lo_u32 v0, v4, v5
	v_mul_hi_u32 v0, v5, v0
	v_add_u32_e32 v0, v5, v0
	v_mul_hi_u32 v0, v6, v0
	v_mul_lo_u32 v4, v0, v3
	v_sub_u32_e32 v4, v6, v4
	v_add_u32_e32 v5, 1, v0
	v_cmp_ge_u32_e32 vcc, v4, v3
	s_nop 1
	v_cndmask_b32_e32 v0, v0, v5, vcc
	v_sub_u32_e32 v5, v4, v3
	v_cndmask_b32_e32 v4, v4, v5, vcc
	v_add_u32_e32 v5, 1, v0
	v_cmp_ge_u32_e32 vcc, v4, v3
	v_add_u32_e32 v4, 1, v6
	s_nop 0
	v_cndmask_b32_e32 v0, v0, v5, vcc
	v_mul_lo_u32 v5, v3, v0
	v_add_u32_e32 v3, v5, v3
	v_cmp_ne_u32_e32 vcc, v4, v3
	s_and_saveexec_b64 s[18:19], vcc
	s_xor_b64 s[18:19], exec, s[18:19]
	s_cbranch_execz .LBB0_1058
	s_waitcnt lgkmcnt(0)
	global_load_dword v2, v1, s[54:55] sc1
	s_waitcnt vmcnt(0)
	v_cmp_eq_u32_e32 vcc, v2, v0
	s_and_saveexec_b64 s[24:25], vcc
	s_cbranch_execz .LBB0_1057
	s_mov_b32 s1, 1
	s_mov_b64 s[26:27], 0
	s_branch .LBB0_1048
